# static priority A/B: mixer phases run with no priority raise for waves 4-7 (after the mask/decay rewrites the raised half no longer needs it)
# baseline (speedup 1.0000x reference)
.LBB0_106:
	v_readfirstlane_b32 s0, v250
	s_cmpk_lt_u32 s0, 0x100
	s_cbranch_scc1 .LBB0_109
	s_setprio 0
	s_bitcmp0_b32 s74, 0
	s_mov_b64 s[0:1], -1
	s_cbranch_scc0 .LBB0_110
